# v65 + wide in-projection k-loop: 12 MFMAs after the barrier (same split as up/down)
# speedup vs baseline: 1.0045x; 1.0012x over previous
.LBB0_124:
	s_waitcnt lgkmcnt(0)
	s_mov_b32 s99, 0x10000
	s_mov_b32 s100, 0x80
	s_mov_b32 s101, 0
	s_add_i32 m0, s4, 0x10000
	s_nop 0
	global_load_lds_dwordx4 v[130:131], off
	v_lshl_add_u64 v[130:131], v[130:131], 0, s[100:101]
	s_add_i32 m0, s4, 0x18000
	s_nop 0
	global_load_lds_dwordx4 v[138:139], off
	v_lshl_add_u64 v[138:139], v[138:139], 0, s[100:101]
	s_add_i32 m0, s5, 0x10000
	s_nop 0
	global_load_lds_dwordx4 v[132:133], off
	v_lshl_add_u64 v[132:133], v[132:133], 0, s[100:101]
	s_add_i32 m0, s5, 0x18000
	s_nop 0
	global_load_lds_dwordx4 v[140:141], off
	v_lshl_add_u64 v[140:141], v[140:141], 0, s[100:101]
	s_add_i32 m0, s6, 0x10000
	s_nop 0
	global_load_lds_dwordx4 v[134:135], off
	v_lshl_add_u64 v[134:135], v[134:135], 0, s[100:101]
	s_add_i32 m0, s6, 0x18000
	s_nop 0
	global_load_lds_dwordx4 v[142:143], off
	v_lshl_add_u64 v[142:143], v[142:143], 0, s[100:101]
	s_add_i32 m0, s7, 0x10000
	s_nop 0
	global_load_lds_dwordx4 v[136:137], off
	v_lshl_add_u64 v[136:137], v[136:137], 0, s[100:101]
	s_add_i32 m0, s7, 0x18000
	s_nop 0
	global_load_lds_dwordx4 v[144:145], off
	v_lshl_add_u64 v[144:145], v[144:145], 0, s[100:101]
	v_add_u32_e32 v162, v149, v147
	v_add_u32_e32 v128, v149, v146
	ds_read_b128 v[150:153], v162 offset:32768
	ds_read_b128 v[154:157], v162 offset:34816
	ds_read_b128 v[158:161], v162 offset:36864
	ds_read_b128 v[162:165], v162 offset:38912
	ds_read_b128 v[166:169], v128 offset:0
	ds_read_b128 v[170:173], v128 offset:2048
	ds_read_b128 v[174:177], v128 offset:4096
	ds_read_b128 v[180:183], v128 offset:6144
	ds_read_b128 v[186:189], v128 offset:8192
	ds_read_b128 v[190:193], v128 offset:10240
	ds_read_b128 v[194:197], v128 offset:12288
	ds_read_b128 v[198:201], v128 offset:14336
	s_waitcnt lgkmcnt(4)
	v_mfma_f32_16x16x32_bf16 v[124:127], v[166:169], v[150:153], 0
	v_mfma_f32_16x16x32_bf16 v[120:123], v[166:169], v[154:157], 0
	v_mfma_f32_16x16x32_bf16 v[116:119], v[166:169], v[158:161], 0
	v_mfma_f32_16x16x32_bf16 v[112:115], v[166:169], v[162:165], 0
	v_mfma_f32_16x16x32_bf16 v[108:111], v[170:173], v[150:153], 0
	v_mfma_f32_16x16x32_bf16 v[104:107], v[170:173], v[154:157], 0
	v_mfma_f32_16x16x32_bf16 v[100:103], v[170:173], v[158:161], 0
	v_mfma_f32_16x16x32_bf16 v[96:99], v[170:173], v[162:165], 0
	v_mfma_f32_16x16x32_bf16 v[92:95], v[174:177], v[150:153], 0
	v_mfma_f32_16x16x32_bf16 v[84:87], v[174:177], v[154:157], 0
	v_mfma_f32_16x16x32_bf16 v[80:83], v[174:177], v[158:161], 0
	v_mfma_f32_16x16x32_bf16 v[76:79], v[174:177], v[162:165], 0
	v_mfma_f32_16x16x32_bf16 v[72:75], v[180:183], v[150:153], 0
	v_mfma_f32_16x16x32_bf16 v[68:71], v[180:183], v[154:157], 0
	v_mfma_f32_16x16x32_bf16 v[64:67], v[180:183], v[158:161], 0
	v_mfma_f32_16x16x32_bf16 v[60:63], v[180:183], v[162:165], 0
	v_add_u32_e32 v180, v148, v147
	v_add_u32_e32 v128, v148, v146
	ds_read_b128 v[166:169], v180 offset:32768
	ds_read_b128 v[170:173], v180 offset:34816
	ds_read_b128 v[174:177], v180 offset:36864
	ds_read_b128 v[180:183], v180 offset:38912
	ds_read_b128 v[202:205], v128 offset:0
	ds_read_b128 v[206:209], v128 offset:2048
	ds_read_b128 v[210:213], v128 offset:4096
	ds_read_b128 v[214:217], v128 offset:6144
	s_waitcnt lgkmcnt(8)
	v_mfma_f32_16x16x32_bf16 v[56:59], v[186:189], v[150:153], 0
	v_mfma_f32_16x16x32_bf16 v[52:55], v[186:189], v[154:157], 0
	v_mfma_f32_16x16x32_bf16 v[48:51], v[186:189], v[158:161], 0
	v_mfma_f32_16x16x32_bf16 v[44:47], v[186:189], v[162:165], 0
	v_mfma_f32_16x16x32_bf16 v[40:43], v[190:193], v[150:153], 0
	v_mfma_f32_16x16x32_bf16 v[36:39], v[190:193], v[154:157], 0
	v_mfma_f32_16x16x32_bf16 v[32:35], v[190:193], v[158:161], 0
	v_mfma_f32_16x16x32_bf16 v[28:31], v[190:193], v[162:165], 0
	v_mfma_f32_16x16x32_bf16 v[24:27], v[194:197], v[150:153], 0
	v_mfma_f32_16x16x32_bf16 v[20:23], v[194:197], v[154:157], 0
	v_mfma_f32_16x16x32_bf16 v[16:19], v[194:197], v[158:161], 0
	v_mfma_f32_16x16x32_bf16 v[12:15], v[194:197], v[162:165], 0
	v_mfma_f32_16x16x32_bf16 v[8:11], v[198:201], v[150:153], 0
	v_mfma_f32_16x16x32_bf16 v[4:7], v[198:201], v[154:157], 0
	v_mfma_f32_16x16x32_bf16 v[0:3], v[198:201], v[158:161], 0
	v_mfma_f32_16x16x32_bf16 v[88:91], v[198:201], v[162:165], 0
	ds_read_b128 v[150:153], v128 offset:8192
	ds_read_b128 v[154:157], v128 offset:10240
	ds_read_b128 v[158:161], v128 offset:12288
	ds_read_b128 v[162:165], v128 offset:14336
	s_waitcnt lgkmcnt(4)
	v_mfma_f32_16x16x32_bf16 v[124:127], v[202:205], v[166:169], v[124:127]
	v_mfma_f32_16x16x32_bf16 v[120:123], v[202:205], v[170:173], v[120:123]
	v_mfma_f32_16x16x32_bf16 v[116:119], v[202:205], v[174:177], v[116:119]
	v_mfma_f32_16x16x32_bf16 v[112:115], v[202:205], v[180:183], v[112:115]
	v_mfma_f32_16x16x32_bf16 v[108:111], v[206:209], v[166:169], v[108:111]
	v_mfma_f32_16x16x32_bf16 v[104:107], v[206:209], v[170:173], v[104:107]
	v_mfma_f32_16x16x32_bf16 v[100:103], v[206:209], v[174:177], v[100:103]
	v_mfma_f32_16x16x32_bf16 v[96:99], v[206:209], v[180:183], v[96:99]
	v_mfma_f32_16x16x32_bf16 v[92:95], v[210:213], v[166:169], v[92:95]
	v_mfma_f32_16x16x32_bf16 v[84:87], v[210:213], v[170:173], v[84:87]
	v_mfma_f32_16x16x32_bf16 v[80:83], v[210:213], v[174:177], v[80:83]
	v_mfma_f32_16x16x32_bf16 v[76:79], v[210:213], v[180:183], v[76:79]
	v_mfma_f32_16x16x32_bf16 v[72:75], v[214:217], v[166:169], v[72:75]
	v_mfma_f32_16x16x32_bf16 v[68:71], v[214:217], v[170:173], v[68:71]
	v_mfma_f32_16x16x32_bf16 v[64:67], v[214:217], v[174:177], v[64:67]
	v_mfma_f32_16x16x32_bf16 v[60:63], v[214:217], v[180:183], v[60:63]
	s_waitcnt lgkmcnt(0)
	v_mfma_f32_16x16x32_bf16 v[56:59], v[150:153], v[166:169], v[56:59]
	v_mfma_f32_16x16x32_bf16 v[52:55], v[150:153], v[170:173], v[52:55]
	v_mfma_f32_16x16x32_bf16 v[48:51], v[150:153], v[174:177], v[48:51]
	v_mfma_f32_16x16x32_bf16 v[44:47], v[150:153], v[180:183], v[44:47]
	s_waitcnt vmcnt(0)
	s_barrier
	v_add3_u32 v198, v149, v147, s99
	v_add3_u32 v128, v149, v146, s99
	v_mfma_f32_16x16x32_bf16 v[40:43], v[154:157], v[166:169], v[40:43]
	ds_read_b128 v[186:189], v198 offset:32768
	ds_read_b128 v[190:193], v198 offset:34816
	v_mfma_f32_16x16x32_bf16 v[36:39], v[154:157], v[170:173], v[36:39]
	ds_read_b128 v[194:197], v198 offset:36864
	ds_read_b128 v[198:201], v198 offset:38912
	v_mfma_f32_16x16x32_bf16 v[32:35], v[154:157], v[174:177], v[32:35]
	ds_read_b128 v[202:205], v128 offset:0
	ds_read_b128 v[206:209], v128 offset:2048
	v_mfma_f32_16x16x32_bf16 v[28:31], v[154:157], v[180:183], v[28:31]
	ds_read_b128 v[210:213], v128 offset:4096
	ds_read_b128 v[214:217], v128 offset:6144
	s_mov_b32 m0, s4
	v_mfma_f32_16x16x32_bf16 v[24:27], v[158:161], v[166:169], v[24:27]
	global_load_lds_dwordx4 v[130:131], off
	v_lshl_add_u64 v[130:131], v[130:131], 0, s[100:101]
	s_add_i32 m0, s4, 0x8000
	v_mfma_f32_16x16x32_bf16 v[20:23], v[158:161], v[170:173], v[20:23]
	global_load_lds_dwordx4 v[138:139], off
	v_lshl_add_u64 v[138:139], v[138:139], 0, s[100:101]
	s_mov_b32 m0, s5
	v_mfma_f32_16x16x32_bf16 v[16:19], v[158:161], v[174:177], v[16:19]
	global_load_lds_dwordx4 v[132:133], off
	v_lshl_add_u64 v[132:133], v[132:133], 0, s[100:101]
	s_add_i32 m0, s5, 0x8000
	v_mfma_f32_16x16x32_bf16 v[12:15], v[158:161], v[180:183], v[12:15]
	global_load_lds_dwordx4 v[140:141], off
	v_lshl_add_u64 v[140:141], v[140:141], 0, s[100:101]
	s_mov_b32 m0, s6
	v_mfma_f32_16x16x32_bf16 v[8:11], v[162:165], v[166:169], v[8:11]
	global_load_lds_dwordx4 v[134:135], off
	v_lshl_add_u64 v[134:135], v[134:135], 0, s[100:101]
	s_add_i32 m0, s6, 0x8000
	v_mfma_f32_16x16x32_bf16 v[4:7], v[162:165], v[170:173], v[4:7]
	global_load_lds_dwordx4 v[142:143], off
	v_lshl_add_u64 v[142:143], v[142:143], 0, s[100:101]
	s_mov_b32 m0, s7
	v_mfma_f32_16x16x32_bf16 v[0:3], v[162:165], v[174:177], v[0:3]
	global_load_lds_dwordx4 v[136:137], off
	v_lshl_add_u64 v[136:137], v[136:137], 0, s[100:101]
	s_add_i32 m0, s7, 0x8000
	v_mfma_f32_16x16x32_bf16 v[88:91], v[162:165], v[180:183], v[88:91]
	global_load_lds_dwordx4 v[144:145], off
	v_lshl_add_u64 v[144:145], v[144:145], 0, s[100:101]
	ds_read_b128 v[150:153], v128 offset:8192
	ds_read_b128 v[154:157], v128 offset:10240
	ds_read_b128 v[158:161], v128 offset:12288
	ds_read_b128 v[162:165], v128 offset:14336
	s_waitcnt lgkmcnt(4)
	v_mfma_f32_16x16x32_bf16 v[124:127], v[202:205], v[186:189], v[124:127]
	v_mfma_f32_16x16x32_bf16 v[120:123], v[202:205], v[190:193], v[120:123]
	v_mfma_f32_16x16x32_bf16 v[116:119], v[202:205], v[194:197], v[116:119]
	v_mfma_f32_16x16x32_bf16 v[112:115], v[202:205], v[198:201], v[112:115]
	v_mfma_f32_16x16x32_bf16 v[108:111], v[206:209], v[186:189], v[108:111]
	v_mfma_f32_16x16x32_bf16 v[104:107], v[206:209], v[190:193], v[104:107]
	v_mfma_f32_16x16x32_bf16 v[100:103], v[206:209], v[194:197], v[100:103]
	v_mfma_f32_16x16x32_bf16 v[96:99], v[206:209], v[198:201], v[96:99]
	v_mfma_f32_16x16x32_bf16 v[92:95], v[210:213], v[186:189], v[92:95]
	v_mfma_f32_16x16x32_bf16 v[84:87], v[210:213], v[190:193], v[84:87]
	v_mfma_f32_16x16x32_bf16 v[80:83], v[210:213], v[194:197], v[80:83]
	v_mfma_f32_16x16x32_bf16 v[76:79], v[210:213], v[198:201], v[76:79]
	v_mfma_f32_16x16x32_bf16 v[72:75], v[214:217], v[186:189], v[72:75]
	v_mfma_f32_16x16x32_bf16 v[68:71], v[214:217], v[190:193], v[68:71]
	v_mfma_f32_16x16x32_bf16 v[64:67], v[214:217], v[194:197], v[64:67]
	v_mfma_f32_16x16x32_bf16 v[60:63], v[214:217], v[198:201], v[60:63]
	v_add3_u32 v214, v148, v147, s99
	v_add3_u32 v128, v148, v146, s99
	ds_read_b128 v[202:205], v214 offset:32768
	ds_read_b128 v[206:209], v214 offset:34816
	ds_read_b128 v[210:213], v214 offset:36864
	ds_read_b128 v[214:217], v214 offset:38912
	ds_read_b128 v[166:169], v128 offset:0
	ds_read_b128 v[170:173], v128 offset:2048
	ds_read_b128 v[174:177], v128 offset:4096
	ds_read_b128 v[180:183], v128 offset:6144
	s_waitcnt lgkmcnt(8)
	v_mfma_f32_16x16x32_bf16 v[56:59], v[150:153], v[186:189], v[56:59]
	v_mfma_f32_16x16x32_bf16 v[52:55], v[150:153], v[190:193], v[52:55]
	v_mfma_f32_16x16x32_bf16 v[48:51], v[150:153], v[194:197], v[48:51]
	v_mfma_f32_16x16x32_bf16 v[44:47], v[150:153], v[198:201], v[44:47]
	v_mfma_f32_16x16x32_bf16 v[40:43], v[154:157], v[186:189], v[40:43]
	v_mfma_f32_16x16x32_bf16 v[36:39], v[154:157], v[190:193], v[36:39]
	v_mfma_f32_16x16x32_bf16 v[32:35], v[154:157], v[194:197], v[32:35]
	v_mfma_f32_16x16x32_bf16 v[28:31], v[154:157], v[198:201], v[28:31]
	v_mfma_f32_16x16x32_bf16 v[24:27], v[158:161], v[186:189], v[24:27]
	v_mfma_f32_16x16x32_bf16 v[20:23], v[158:161], v[190:193], v[20:23]
	v_mfma_f32_16x16x32_bf16 v[16:19], v[158:161], v[194:197], v[16:19]
	v_mfma_f32_16x16x32_bf16 v[12:15], v[158:161], v[198:201], v[12:15]
	v_mfma_f32_16x16x32_bf16 v[8:11], v[162:165], v[186:189], v[8:11]
	v_mfma_f32_16x16x32_bf16 v[4:7], v[162:165], v[190:193], v[4:7]
	v_mfma_f32_16x16x32_bf16 v[0:3], v[162:165], v[194:197], v[0:3]
	v_mfma_f32_16x16x32_bf16 v[88:91], v[162:165], v[198:201], v[88:91]
	ds_read_b128 v[186:189], v128 offset:8192
	ds_read_b128 v[190:193], v128 offset:10240
	ds_read_b128 v[194:197], v128 offset:12288
	ds_read_b128 v[198:201], v128 offset:14336
	s_waitcnt lgkmcnt(4)
	v_mfma_f32_16x16x32_bf16 v[124:127], v[166:169], v[202:205], v[124:127]
	v_mfma_f32_16x16x32_bf16 v[120:123], v[166:169], v[206:209], v[120:123]
	v_mfma_f32_16x16x32_bf16 v[116:119], v[166:169], v[210:213], v[116:119]
	v_mfma_f32_16x16x32_bf16 v[112:115], v[166:169], v[214:217], v[112:115]
	v_mfma_f32_16x16x32_bf16 v[108:111], v[170:173], v[202:205], v[108:111]
	v_mfma_f32_16x16x32_bf16 v[104:107], v[170:173], v[206:209], v[104:107]
	v_mfma_f32_16x16x32_bf16 v[100:103], v[170:173], v[210:213], v[100:103]
	v_mfma_f32_16x16x32_bf16 v[96:99], v[170:173], v[214:217], v[96:99]
	v_mfma_f32_16x16x32_bf16 v[92:95], v[174:177], v[202:205], v[92:95]
	v_mfma_f32_16x16x32_bf16 v[84:87], v[174:177], v[206:209], v[84:87]
	v_mfma_f32_16x16x32_bf16 v[80:83], v[174:177], v[210:213], v[80:83]
	v_mfma_f32_16x16x32_bf16 v[76:79], v[174:177], v[214:217], v[76:79]
	v_mfma_f32_16x16x32_bf16 v[72:75], v[180:183], v[202:205], v[72:75]
	v_mfma_f32_16x16x32_bf16 v[68:71], v[180:183], v[206:209], v[68:71]
	v_mfma_f32_16x16x32_bf16 v[64:67], v[180:183], v[210:213], v[64:67]
	v_mfma_f32_16x16x32_bf16 v[60:63], v[180:183], v[214:217], v[60:63]
	s_waitcnt lgkmcnt(0)
	v_mfma_f32_16x16x32_bf16 v[56:59], v[186:189], v[202:205], v[56:59]
	v_mfma_f32_16x16x32_bf16 v[52:55], v[186:189], v[206:209], v[52:55]
	v_mfma_f32_16x16x32_bf16 v[48:51], v[186:189], v[210:213], v[48:51]
	v_mfma_f32_16x16x32_bf16 v[44:47], v[186:189], v[214:217], v[44:47]
	s_waitcnt vmcnt(0)
	s_barrier
	v_add_u32_e32 v162, v149, v147
	v_add_u32_e32 v128, v149, v146
	v_mfma_f32_16x16x32_bf16 v[40:43], v[190:193], v[202:205], v[40:43]
	ds_read_b128 v[150:153], v162 offset:32768
	ds_read_b128 v[154:157], v162 offset:34816
	v_mfma_f32_16x16x32_bf16 v[36:39], v[190:193], v[206:209], v[36:39]
	ds_read_b128 v[158:161], v162 offset:36864
	ds_read_b128 v[162:165], v162 offset:38912
	v_mfma_f32_16x16x32_bf16 v[32:35], v[190:193], v[210:213], v[32:35]
	ds_read_b128 v[166:169], v128 offset:0
	ds_read_b128 v[170:173], v128 offset:2048
	v_mfma_f32_16x16x32_bf16 v[28:31], v[190:193], v[214:217], v[28:31]
	ds_read_b128 v[174:177], v128 offset:4096
	ds_read_b128 v[180:183], v128 offset:6144
	s_add_i32 m0, s4, 0x10000
	v_mfma_f32_16x16x32_bf16 v[24:27], v[194:197], v[202:205], v[24:27]
	global_load_lds_dwordx4 v[130:131], off
	v_lshl_add_u64 v[130:131], v[130:131], 0, s[100:101]
	s_add_i32 m0, s4, 0x18000
	v_mfma_f32_16x16x32_bf16 v[20:23], v[194:197], v[206:209], v[20:23]
	global_load_lds_dwordx4 v[138:139], off
	v_lshl_add_u64 v[138:139], v[138:139], 0, s[100:101]
	s_add_i32 m0, s5, 0x10000
	v_mfma_f32_16x16x32_bf16 v[16:19], v[194:197], v[210:213], v[16:19]
	global_load_lds_dwordx4 v[132:133], off
	v_lshl_add_u64 v[132:133], v[132:133], 0, s[100:101]
	s_add_i32 m0, s5, 0x18000
	v_mfma_f32_16x16x32_bf16 v[12:15], v[194:197], v[214:217], v[12:15]
	global_load_lds_dwordx4 v[140:141], off
	v_lshl_add_u64 v[140:141], v[140:141], 0, s[100:101]
	s_add_i32 m0, s6, 0x10000
	v_mfma_f32_16x16x32_bf16 v[8:11], v[198:201], v[202:205], v[8:11]
	global_load_lds_dwordx4 v[134:135], off
	v_lshl_add_u64 v[134:135], v[134:135], 0, s[100:101]
	s_add_i32 m0, s6, 0x18000
	v_mfma_f32_16x16x32_bf16 v[4:7], v[198:201], v[206:209], v[4:7]
	global_load_lds_dwordx4 v[142:143], off
	v_lshl_add_u64 v[142:143], v[142:143], 0, s[100:101]
	s_add_i32 m0, s7, 0x10000
	v_mfma_f32_16x16x32_bf16 v[0:3], v[198:201], v[210:213], v[0:3]
	global_load_lds_dwordx4 v[136:137], off
	v_lshl_add_u64 v[136:137], v[136:137], 0, s[100:101]
	s_add_i32 m0, s7, 0x18000
	v_mfma_f32_16x16x32_bf16 v[88:91], v[198:201], v[214:217], v[88:91]
	global_load_lds_dwordx4 v[144:145], off
	v_lshl_add_u64 v[144:145], v[144:145], 0, s[100:101]
	s_movk_i32 s2, 0x100
.Lg_inproj_loop:
	ds_read_b128 v[186:189], v128 offset:8192
	ds_read_b128 v[190:193], v128 offset:10240
	ds_read_b128 v[194:197], v128 offset:12288
	ds_read_b128 v[198:201], v128 offset:14336
	s_waitcnt lgkmcnt(4)
	v_mfma_f32_16x16x32_bf16 v[124:127], v[166:169], v[150:153], v[124:127]
	v_mfma_f32_16x16x32_bf16 v[120:123], v[166:169], v[154:157], v[120:123]
	v_mfma_f32_16x16x32_bf16 v[116:119], v[166:169], v[158:161], v[116:119]
	v_mfma_f32_16x16x32_bf16 v[112:115], v[166:169], v[162:165], v[112:115]
	v_mfma_f32_16x16x32_bf16 v[108:111], v[170:173], v[150:153], v[108:111]
	v_mfma_f32_16x16x32_bf16 v[104:107], v[170:173], v[154:157], v[104:107]
	v_mfma_f32_16x16x32_bf16 v[100:103], v[170:173], v[158:161], v[100:103]
	v_mfma_f32_16x16x32_bf16 v[96:99], v[170:173], v[162:165], v[96:99]
	v_mfma_f32_16x16x32_bf16 v[92:95], v[174:177], v[150:153], v[92:95]
	v_mfma_f32_16x16x32_bf16 v[84:87], v[174:177], v[154:157], v[84:87]
	v_mfma_f32_16x16x32_bf16 v[80:83], v[174:177], v[158:161], v[80:83]
	v_mfma_f32_16x16x32_bf16 v[76:79], v[174:177], v[162:165], v[76:79]
	v_mfma_f32_16x16x32_bf16 v[72:75], v[180:183], v[150:153], v[72:75]
	v_mfma_f32_16x16x32_bf16 v[68:71], v[180:183], v[154:157], v[68:71]
	v_mfma_f32_16x16x32_bf16 v[64:67], v[180:183], v[158:161], v[64:67]
	v_mfma_f32_16x16x32_bf16 v[60:63], v[180:183], v[162:165], v[60:63]
	v_add_u32_e32 v180, v148, v147
	v_add_u32_e32 v128, v148, v146
	ds_read_b128 v[166:169], v180 offset:32768
	ds_read_b128 v[170:173], v180 offset:34816
	ds_read_b128 v[174:177], v180 offset:36864
	ds_read_b128 v[180:183], v180 offset:38912
	ds_read_b128 v[202:205], v128 offset:0
	ds_read_b128 v[206:209], v128 offset:2048
	ds_read_b128 v[210:213], v128 offset:4096
	ds_read_b128 v[214:217], v128 offset:6144
	s_waitcnt lgkmcnt(8)
	v_mfma_f32_16x16x32_bf16 v[56:59], v[186:189], v[150:153], v[56:59]
	v_mfma_f32_16x16x32_bf16 v[52:55], v[186:189], v[154:157], v[52:55]
	v_mfma_f32_16x16x32_bf16 v[48:51], v[186:189], v[158:161], v[48:51]
	v_mfma_f32_16x16x32_bf16 v[44:47], v[186:189], v[162:165], v[44:47]
	v_mfma_f32_16x16x32_bf16 v[40:43], v[190:193], v[150:153], v[40:43]
	v_mfma_f32_16x16x32_bf16 v[36:39], v[190:193], v[154:157], v[36:39]
	v_mfma_f32_16x16x32_bf16 v[32:35], v[190:193], v[158:161], v[32:35]
	v_mfma_f32_16x16x32_bf16 v[28:31], v[190:193], v[162:165], v[28:31]
	v_mfma_f32_16x16x32_bf16 v[24:27], v[194:197], v[150:153], v[24:27]
	v_mfma_f32_16x16x32_bf16 v[20:23], v[194:197], v[154:157], v[20:23]
	v_mfma_f32_16x16x32_bf16 v[16:19], v[194:197], v[158:161], v[16:19]
	v_mfma_f32_16x16x32_bf16 v[12:15], v[194:197], v[162:165], v[12:15]
	v_mfma_f32_16x16x32_bf16 v[8:11], v[198:201], v[150:153], v[8:11]
	v_mfma_f32_16x16x32_bf16 v[4:7], v[198:201], v[154:157], v[4:7]
	v_mfma_f32_16x16x32_bf16 v[0:3], v[198:201], v[158:161], v[0:3]
	v_mfma_f32_16x16x32_bf16 v[88:91], v[198:201], v[162:165], v[88:91]
	ds_read_b128 v[150:153], v128 offset:8192
	ds_read_b128 v[154:157], v128 offset:10240
	ds_read_b128 v[158:161], v128 offset:12288
	ds_read_b128 v[162:165], v128 offset:14336
	s_waitcnt lgkmcnt(4)
	v_mfma_f32_16x16x32_bf16 v[124:127], v[202:205], v[166:169], v[124:127]
	v_mfma_f32_16x16x32_bf16 v[120:123], v[202:205], v[170:173], v[120:123]
	v_mfma_f32_16x16x32_bf16 v[116:119], v[202:205], v[174:177], v[116:119]
	v_mfma_f32_16x16x32_bf16 v[112:115], v[202:205], v[180:183], v[112:115]
	v_mfma_f32_16x16x32_bf16 v[108:111], v[206:209], v[166:169], v[108:111]
	v_mfma_f32_16x16x32_bf16 v[104:107], v[206:209], v[170:173], v[104:107]
	v_mfma_f32_16x16x32_bf16 v[100:103], v[206:209], v[174:177], v[100:103]
	v_mfma_f32_16x16x32_bf16 v[96:99], v[206:209], v[180:183], v[96:99]
	v_mfma_f32_16x16x32_bf16 v[92:95], v[210:213], v[166:169], v[92:95]
	v_mfma_f32_16x16x32_bf16 v[84:87], v[210:213], v[170:173], v[84:87]
	v_mfma_f32_16x16x32_bf16 v[80:83], v[210:213], v[174:177], v[80:83]
	v_mfma_f32_16x16x32_bf16 v[76:79], v[210:213], v[180:183], v[76:79]
	v_mfma_f32_16x16x32_bf16 v[72:75], v[214:217], v[166:169], v[72:75]
	v_mfma_f32_16x16x32_bf16 v[68:71], v[214:217], v[170:173], v[68:71]
	v_mfma_f32_16x16x32_bf16 v[64:67], v[214:217], v[174:177], v[64:67]
	v_mfma_f32_16x16x32_bf16 v[60:63], v[214:217], v[180:183], v[60:63]
	s_waitcnt lgkmcnt(0)
	v_mfma_f32_16x16x32_bf16 v[56:59], v[150:153], v[166:169], v[56:59]
	v_mfma_f32_16x16x32_bf16 v[52:55], v[150:153], v[170:173], v[52:55]
	v_mfma_f32_16x16x32_bf16 v[48:51], v[150:153], v[174:177], v[48:51]
	v_mfma_f32_16x16x32_bf16 v[44:47], v[150:153], v[180:183], v[44:47]
	s_waitcnt vmcnt(0)
	s_barrier
	v_add3_u32 v198, v149, v147, s99
	v_add3_u32 v128, v149, v146, s99
	v_mfma_f32_16x16x32_bf16 v[40:43], v[154:157], v[166:169], v[40:43]
	ds_read_b128 v[186:189], v198 offset:32768
	ds_read_b128 v[190:193], v198 offset:34816
	v_mfma_f32_16x16x32_bf16 v[36:39], v[154:157], v[170:173], v[36:39]
	ds_read_b128 v[194:197], v198 offset:36864
	ds_read_b128 v[198:201], v198 offset:38912
	v_mfma_f32_16x16x32_bf16 v[32:35], v[154:157], v[174:177], v[32:35]
	ds_read_b128 v[202:205], v128 offset:0
	ds_read_b128 v[206:209], v128 offset:2048
	v_mfma_f32_16x16x32_bf16 v[28:31], v[154:157], v[180:183], v[28:31]
	ds_read_b128 v[210:213], v128 offset:4096
	ds_read_b128 v[214:217], v128 offset:6144
	s_mov_b32 m0, s4
	v_mfma_f32_16x16x32_bf16 v[24:27], v[158:161], v[166:169], v[24:27]
	global_load_lds_dwordx4 v[130:131], off
	v_lshl_add_u64 v[130:131], v[130:131], 0, s[100:101]
	s_add_i32 m0, s4, 0x8000
	v_mfma_f32_16x16x32_bf16 v[20:23], v[158:161], v[170:173], v[20:23]
	global_load_lds_dwordx4 v[138:139], off
	v_lshl_add_u64 v[138:139], v[138:139], 0, s[100:101]
	s_mov_b32 m0, s5
	v_mfma_f32_16x16x32_bf16 v[16:19], v[158:161], v[174:177], v[16:19]
	global_load_lds_dwordx4 v[132:133], off
	v_lshl_add_u64 v[132:133], v[132:133], 0, s[100:101]
	s_add_i32 m0, s5, 0x8000
	v_mfma_f32_16x16x32_bf16 v[12:15], v[158:161], v[180:183], v[12:15]
	global_load_lds_dwordx4 v[140:141], off
	v_lshl_add_u64 v[140:141], v[140:141], 0, s[100:101]
	s_mov_b32 m0, s6
	v_mfma_f32_16x16x32_bf16 v[8:11], v[162:165], v[166:169], v[8:11]
	global_load_lds_dwordx4 v[134:135], off
	v_lshl_add_u64 v[134:135], v[134:135], 0, s[100:101]
	s_add_i32 m0, s6, 0x8000
	v_mfma_f32_16x16x32_bf16 v[4:7], v[162:165], v[170:173], v[4:7]
	global_load_lds_dwordx4 v[142:143], off
	v_lshl_add_u64 v[142:143], v[142:143], 0, s[100:101]
	s_mov_b32 m0, s7
	v_mfma_f32_16x16x32_bf16 v[0:3], v[162:165], v[174:177], v[0:3]
	global_load_lds_dwordx4 v[136:137], off
	v_lshl_add_u64 v[136:137], v[136:137], 0, s[100:101]
	s_add_i32 m0, s7, 0x8000
	v_mfma_f32_16x16x32_bf16 v[88:91], v[162:165], v[180:183], v[88:91]
	global_load_lds_dwordx4 v[144:145], off
	v_lshl_add_u64 v[144:145], v[144:145], 0, s[100:101]
	ds_read_b128 v[150:153], v128 offset:8192
	ds_read_b128 v[154:157], v128 offset:10240
	ds_read_b128 v[158:161], v128 offset:12288
	ds_read_b128 v[162:165], v128 offset:14336
	s_waitcnt lgkmcnt(4)
	v_mfma_f32_16x16x32_bf16 v[124:127], v[202:205], v[186:189], v[124:127]
	v_mfma_f32_16x16x32_bf16 v[120:123], v[202:205], v[190:193], v[120:123]
	v_mfma_f32_16x16x32_bf16 v[116:119], v[202:205], v[194:197], v[116:119]
	v_mfma_f32_16x16x32_bf16 v[112:115], v[202:205], v[198:201], v[112:115]
	v_mfma_f32_16x16x32_bf16 v[108:111], v[206:209], v[186:189], v[108:111]
	v_mfma_f32_16x16x32_bf16 v[104:107], v[206:209], v[190:193], v[104:107]
	v_mfma_f32_16x16x32_bf16 v[100:103], v[206:209], v[194:197], v[100:103]
	v_mfma_f32_16x16x32_bf16 v[96:99], v[206:209], v[198:201], v[96:99]
	v_mfma_f32_16x16x32_bf16 v[92:95], v[210:213], v[186:189], v[92:95]
	v_mfma_f32_16x16x32_bf16 v[84:87], v[210:213], v[190:193], v[84:87]
	v_mfma_f32_16x16x32_bf16 v[80:83], v[210:213], v[194:197], v[80:83]
	v_mfma_f32_16x16x32_bf16 v[76:79], v[210:213], v[198:201], v[76:79]
	v_mfma_f32_16x16x32_bf16 v[72:75], v[214:217], v[186:189], v[72:75]
	v_mfma_f32_16x16x32_bf16 v[68:71], v[214:217], v[190:193], v[68:71]
	v_mfma_f32_16x16x32_bf16 v[64:67], v[214:217], v[194:197], v[64:67]
	v_mfma_f32_16x16x32_bf16 v[60:63], v[214:217], v[198:201], v[60:63]
	v_add3_u32 v214, v148, v147, s99
	v_add3_u32 v128, v148, v146, s99
	ds_read_b128 v[202:205], v214 offset:32768
	ds_read_b128 v[206:209], v214 offset:34816
	ds_read_b128 v[210:213], v214 offset:36864
	ds_read_b128 v[214:217], v214 offset:38912
	ds_read_b128 v[166:169], v128 offset:0
	ds_read_b128 v[170:173], v128 offset:2048
	ds_read_b128 v[174:177], v128 offset:4096
	ds_read_b128 v[180:183], v128 offset:6144
	s_waitcnt lgkmcnt(8)
	v_mfma_f32_16x16x32_bf16 v[56:59], v[150:153], v[186:189], v[56:59]
	v_mfma_f32_16x16x32_bf16 v[52:55], v[150:153], v[190:193], v[52:55]
	v_mfma_f32_16x16x32_bf16 v[48:51], v[150:153], v[194:197], v[48:51]
	v_mfma_f32_16x16x32_bf16 v[44:47], v[150:153], v[198:201], v[44:47]
	v_mfma_f32_16x16x32_bf16 v[40:43], v[154:157], v[186:189], v[40:43]
	v_mfma_f32_16x16x32_bf16 v[36:39], v[154:157], v[190:193], v[36:39]
	v_mfma_f32_16x16x32_bf16 v[32:35], v[154:157], v[194:197], v[32:35]
	v_mfma_f32_16x16x32_bf16 v[28:31], v[154:157], v[198:201], v[28:31]
	v_mfma_f32_16x16x32_bf16 v[24:27], v[158:161], v[186:189], v[24:27]
	v_mfma_f32_16x16x32_bf16 v[20:23], v[158:161], v[190:193], v[20:23]
	v_mfma_f32_16x16x32_bf16 v[16:19], v[158:161], v[194:197], v[16:19]
	v_mfma_f32_16x16x32_bf16 v[12:15], v[158:161], v[198:201], v[12:15]
	v_mfma_f32_16x16x32_bf16 v[8:11], v[162:165], v[186:189], v[8:11]
	v_mfma_f32_16x16x32_bf16 v[4:7], v[162:165], v[190:193], v[4:7]
	v_mfma_f32_16x16x32_bf16 v[0:3], v[162:165], v[194:197], v[0:3]
	v_mfma_f32_16x16x32_bf16 v[88:91], v[162:165], v[198:201], v[88:91]
	ds_read_b128 v[186:189], v128 offset:8192
	ds_read_b128 v[190:193], v128 offset:10240
	ds_read_b128 v[194:197], v128 offset:12288
	ds_read_b128 v[198:201], v128 offset:14336
	s_waitcnt lgkmcnt(4)
	v_mfma_f32_16x16x32_bf16 v[124:127], v[166:169], v[202:205], v[124:127]
	v_mfma_f32_16x16x32_bf16 v[120:123], v[166:169], v[206:209], v[120:123]
	v_mfma_f32_16x16x32_bf16 v[116:119], v[166:169], v[210:213], v[116:119]
	v_mfma_f32_16x16x32_bf16 v[112:115], v[166:169], v[214:217], v[112:115]
	v_mfma_f32_16x16x32_bf16 v[108:111], v[170:173], v[202:205], v[108:111]
	v_mfma_f32_16x16x32_bf16 v[104:107], v[170:173], v[206:209], v[104:107]
	v_mfma_f32_16x16x32_bf16 v[100:103], v[170:173], v[210:213], v[100:103]
	v_mfma_f32_16x16x32_bf16 v[96:99], v[170:173], v[214:217], v[96:99]
	v_mfma_f32_16x16x32_bf16 v[92:95], v[174:177], v[202:205], v[92:95]
	v_mfma_f32_16x16x32_bf16 v[84:87], v[174:177], v[206:209], v[84:87]
	v_mfma_f32_16x16x32_bf16 v[80:83], v[174:177], v[210:213], v[80:83]
	v_mfma_f32_16x16x32_bf16 v[76:79], v[174:177], v[214:217], v[76:79]
	v_mfma_f32_16x16x32_bf16 v[72:75], v[180:183], v[202:205], v[72:75]
	v_mfma_f32_16x16x32_bf16 v[68:71], v[180:183], v[206:209], v[68:71]
	v_mfma_f32_16x16x32_bf16 v[64:67], v[180:183], v[210:213], v[64:67]
	v_mfma_f32_16x16x32_bf16 v[60:63], v[180:183], v[214:217], v[60:63]
	s_waitcnt lgkmcnt(0)
	v_mfma_f32_16x16x32_bf16 v[56:59], v[186:189], v[202:205], v[56:59]
	v_mfma_f32_16x16x32_bf16 v[52:55], v[186:189], v[206:209], v[52:55]
	v_mfma_f32_16x16x32_bf16 v[48:51], v[186:189], v[210:213], v[48:51]
	v_mfma_f32_16x16x32_bf16 v[44:47], v[186:189], v[214:217], v[44:47]
	s_waitcnt vmcnt(0)
	s_barrier
	v_add_u32_e32 v162, v149, v147
	v_add_u32_e32 v128, v149, v146
	v_mfma_f32_16x16x32_bf16 v[40:43], v[190:193], v[202:205], v[40:43]
	ds_read_b128 v[150:153], v162 offset:32768
	ds_read_b128 v[154:157], v162 offset:34816
	v_mfma_f32_16x16x32_bf16 v[36:39], v[190:193], v[206:209], v[36:39]
	ds_read_b128 v[158:161], v162 offset:36864
	ds_read_b128 v[162:165], v162 offset:38912
	v_mfma_f32_16x16x32_bf16 v[32:35], v[190:193], v[210:213], v[32:35]
	ds_read_b128 v[166:169], v128 offset:0
	ds_read_b128 v[170:173], v128 offset:2048
	v_mfma_f32_16x16x32_bf16 v[28:31], v[190:193], v[214:217], v[28:31]
	ds_read_b128 v[174:177], v128 offset:4096
	ds_read_b128 v[180:183], v128 offset:6144
	s_add_i32 m0, s4, 0x10000
	v_mfma_f32_16x16x32_bf16 v[24:27], v[194:197], v[202:205], v[24:27]
	global_load_lds_dwordx4 v[130:131], off
	v_lshl_add_u64 v[130:131], v[130:131], 0, s[100:101]
	s_add_i32 m0, s4, 0x18000
	v_mfma_f32_16x16x32_bf16 v[20:23], v[194:197], v[206:209], v[20:23]
	global_load_lds_dwordx4 v[138:139], off
	v_lshl_add_u64 v[138:139], v[138:139], 0, s[100:101]
	s_add_i32 m0, s5, 0x10000
	v_mfma_f32_16x16x32_bf16 v[16:19], v[194:197], v[210:213], v[16:19]
	global_load_lds_dwordx4 v[132:133], off
	v_lshl_add_u64 v[132:133], v[132:133], 0, s[100:101]
	s_add_i32 m0, s5, 0x18000
	v_mfma_f32_16x16x32_bf16 v[12:15], v[194:197], v[214:217], v[12:15]
	global_load_lds_dwordx4 v[140:141], off
	v_lshl_add_u64 v[140:141], v[140:141], 0, s[100:101]
	s_add_i32 m0, s6, 0x10000
	v_mfma_f32_16x16x32_bf16 v[8:11], v[198:201], v[202:205], v[8:11]
	global_load_lds_dwordx4 v[134:135], off
	v_lshl_add_u64 v[134:135], v[134:135], 0, s[100:101]
	s_add_i32 m0, s6, 0x18000
	v_mfma_f32_16x16x32_bf16 v[4:7], v[198:201], v[206:209], v[4:7]
	global_load_lds_dwordx4 v[142:143], off
	v_lshl_add_u64 v[142:143], v[142:143], 0, s[100:101]
	s_add_i32 m0, s7, 0x10000
	v_mfma_f32_16x16x32_bf16 v[0:3], v[198:201], v[210:213], v[0:3]
	global_load_lds_dwordx4 v[136:137], off
	v_lshl_add_u64 v[136:137], v[136:137], 0, s[100:101]
	s_add_i32 m0, s7, 0x18000
	v_mfma_f32_16x16x32_bf16 v[88:91], v[198:201], v[214:217], v[88:91]
	global_load_lds_dwordx4 v[144:145], off
	v_lshl_add_u64 v[144:145], v[144:145], 0, s[100:101]
	s_add_u32 s2, s2, 0x100
	s_cmpk_lg_i32 s2, 0x700
	s_cbranch_scc1 .Lg_inproj_loop
	ds_read_b128 v[186:189], v128 offset:8192
	ds_read_b128 v[190:193], v128 offset:10240
	ds_read_b128 v[194:197], v128 offset:12288
	ds_read_b128 v[198:201], v128 offset:14336
	s_waitcnt lgkmcnt(4)
	v_mfma_f32_16x16x32_bf16 v[124:127], v[166:169], v[150:153], v[124:127]
	v_mfma_f32_16x16x32_bf16 v[120:123], v[166:169], v[154:157], v[120:123]
	v_mfma_f32_16x16x32_bf16 v[116:119], v[166:169], v[158:161], v[116:119]
	v_mfma_f32_16x16x32_bf16 v[112:115], v[166:169], v[162:165], v[112:115]
	v_mfma_f32_16x16x32_bf16 v[108:111], v[170:173], v[150:153], v[108:111]
	v_mfma_f32_16x16x32_bf16 v[104:107], v[170:173], v[154:157], v[104:107]
	v_mfma_f32_16x16x32_bf16 v[100:103], v[170:173], v[158:161], v[100:103]
	v_mfma_f32_16x16x32_bf16 v[96:99], v[170:173], v[162:165], v[96:99]
	v_mfma_f32_16x16x32_bf16 v[92:95], v[174:177], v[150:153], v[92:95]
	v_mfma_f32_16x16x32_bf16 v[84:87], v[174:177], v[154:157], v[84:87]
	v_mfma_f32_16x16x32_bf16 v[80:83], v[174:177], v[158:161], v[80:83]
	v_mfma_f32_16x16x32_bf16 v[76:79], v[174:177], v[162:165], v[76:79]
	v_mfma_f32_16x16x32_bf16 v[72:75], v[180:183], v[150:153], v[72:75]
	v_mfma_f32_16x16x32_bf16 v[68:71], v[180:183], v[154:157], v[68:71]
	v_mfma_f32_16x16x32_bf16 v[64:67], v[180:183], v[158:161], v[64:67]
	v_mfma_f32_16x16x32_bf16 v[60:63], v[180:183], v[162:165], v[60:63]
	v_add_u32_e32 v180, v148, v147
	v_add_u32_e32 v128, v148, v146
	ds_read_b128 v[166:169], v180 offset:32768
	ds_read_b128 v[170:173], v180 offset:34816
	ds_read_b128 v[174:177], v180 offset:36864
	ds_read_b128 v[180:183], v180 offset:38912
	ds_read_b128 v[202:205], v128 offset:0
	ds_read_b128 v[206:209], v128 offset:2048
	ds_read_b128 v[210:213], v128 offset:4096
	ds_read_b128 v[214:217], v128 offset:6144
	s_waitcnt lgkmcnt(8)
	v_mfma_f32_16x16x32_bf16 v[56:59], v[186:189], v[150:153], v[56:59]
	v_mfma_f32_16x16x32_bf16 v[52:55], v[186:189], v[154:157], v[52:55]
	v_mfma_f32_16x16x32_bf16 v[48:51], v[186:189], v[158:161], v[48:51]
	v_mfma_f32_16x16x32_bf16 v[44:47], v[186:189], v[162:165], v[44:47]
	v_mfma_f32_16x16x32_bf16 v[40:43], v[190:193], v[150:153], v[40:43]
	v_mfma_f32_16x16x32_bf16 v[36:39], v[190:193], v[154:157], v[36:39]
	v_mfma_f32_16x16x32_bf16 v[32:35], v[190:193], v[158:161], v[32:35]
	v_mfma_f32_16x16x32_bf16 v[28:31], v[190:193], v[162:165], v[28:31]
	v_mfma_f32_16x16x32_bf16 v[24:27], v[194:197], v[150:153], v[24:27]
	v_mfma_f32_16x16x32_bf16 v[20:23], v[194:197], v[154:157], v[20:23]
	v_mfma_f32_16x16x32_bf16 v[16:19], v[194:197], v[158:161], v[16:19]
	v_mfma_f32_16x16x32_bf16 v[12:15], v[194:197], v[162:165], v[12:15]
	v_mfma_f32_16x16x32_bf16 v[8:11], v[198:201], v[150:153], v[8:11]
	v_mfma_f32_16x16x32_bf16 v[4:7], v[198:201], v[154:157], v[4:7]
	v_mfma_f32_16x16x32_bf16 v[0:3], v[198:201], v[158:161], v[0:3]
	v_mfma_f32_16x16x32_bf16 v[88:91], v[198:201], v[162:165], v[88:91]
	ds_read_b128 v[150:153], v128 offset:8192
	ds_read_b128 v[154:157], v128 offset:10240
	ds_read_b128 v[158:161], v128 offset:12288
	ds_read_b128 v[162:165], v128 offset:14336
	s_waitcnt lgkmcnt(4)
	v_mfma_f32_16x16x32_bf16 v[124:127], v[202:205], v[166:169], v[124:127]
	v_mfma_f32_16x16x32_bf16 v[120:123], v[202:205], v[170:173], v[120:123]
	v_mfma_f32_16x16x32_bf16 v[116:119], v[202:205], v[174:177], v[116:119]
	v_mfma_f32_16x16x32_bf16 v[112:115], v[202:205], v[180:183], v[112:115]
	v_mfma_f32_16x16x32_bf16 v[108:111], v[206:209], v[166:169], v[108:111]
	v_mfma_f32_16x16x32_bf16 v[104:107], v[206:209], v[170:173], v[104:107]
	v_mfma_f32_16x16x32_bf16 v[100:103], v[206:209], v[174:177], v[100:103]
	v_mfma_f32_16x16x32_bf16 v[96:99], v[206:209], v[180:183], v[96:99]
	v_mfma_f32_16x16x32_bf16 v[92:95], v[210:213], v[166:169], v[92:95]
	v_mfma_f32_16x16x32_bf16 v[84:87], v[210:213], v[170:173], v[84:87]
	v_mfma_f32_16x16x32_bf16 v[80:83], v[210:213], v[174:177], v[80:83]
	v_mfma_f32_16x16x32_bf16 v[76:79], v[210:213], v[180:183], v[76:79]
	v_mfma_f32_16x16x32_bf16 v[72:75], v[214:217], v[166:169], v[72:75]
	v_mfma_f32_16x16x32_bf16 v[68:71], v[214:217], v[170:173], v[68:71]
	v_mfma_f32_16x16x32_bf16 v[64:67], v[214:217], v[174:177], v[64:67]
	v_mfma_f32_16x16x32_bf16 v[60:63], v[214:217], v[180:183], v[60:63]
	s_waitcnt lgkmcnt(0)
	v_mfma_f32_16x16x32_bf16 v[56:59], v[150:153], v[166:169], v[56:59]
	v_mfma_f32_16x16x32_bf16 v[52:55], v[150:153], v[170:173], v[52:55]
	v_mfma_f32_16x16x32_bf16 v[48:51], v[150:153], v[174:177], v[48:51]
	v_mfma_f32_16x16x32_bf16 v[44:47], v[150:153], v[180:183], v[44:47]
	s_waitcnt vmcnt(0)
	s_barrier
	v_mfma_f32_16x16x32_bf16 v[40:43], v[154:157], v[166:169], v[40:43]
	v_mfma_f32_16x16x32_bf16 v[36:39], v[154:157], v[170:173], v[36:39]
	v_mfma_f32_16x16x32_bf16 v[32:35], v[154:157], v[174:177], v[32:35]
	v_mfma_f32_16x16x32_bf16 v[28:31], v[154:157], v[180:183], v[28:31]
	v_mfma_f32_16x16x32_bf16 v[24:27], v[158:161], v[166:169], v[24:27]
	v_mfma_f32_16x16x32_bf16 v[20:23], v[158:161], v[170:173], v[20:23]
	v_mfma_f32_16x16x32_bf16 v[16:19], v[158:161], v[174:177], v[16:19]
	v_mfma_f32_16x16x32_bf16 v[12:15], v[158:161], v[180:183], v[12:15]
	v_mfma_f32_16x16x32_bf16 v[8:11], v[162:165], v[166:169], v[8:11]
	v_mfma_f32_16x16x32_bf16 v[4:7], v[162:165], v[170:173], v[4:7]
	v_mfma_f32_16x16x32_bf16 v[0:3], v[162:165], v[174:177], v[0:3]
	v_mfma_f32_16x16x32_bf16 v[88:91], v[162:165], v[180:183], v[88:91]
	s_movk_i32 s2, 0x780
	s_mov_b32 s8, 0xf0000
	s_mov_b32 s10, 0xf0000
	s_mov_b32 s9, 0x10000
	s_add_i32 s11, s7, 0x10000
	v_add_u32_e32 v128, s9, v149
	v_add_u32_e32 v142, v128, v147
	v_add_u32_e32 v128, v128, v146
	ds_read_b128 v[130:133], v142 offset:32768
	ds_read_b128 v[134:137], v142 offset:34816
	ds_read_b128 v[138:141], v142 offset:36864
	ds_read_b128 v[142:145], v142 offset:38912
	ds_read_b128 v[150:153], v128
	ds_read_b128 v[154:157], v128 offset:2048
	ds_read_b128 v[158:161], v128 offset:4096
	ds_read_b128 v[162:165], v128 offset:6144
	ds_read_b128 v[166:169], v128 offset:8192
	ds_read_b128 v[170:173], v128 offset:10240
	ds_read_b128 v[174:177], v128 offset:12288
	ds_read_b128 v[180:183], v128 offset:14336
	s_lshl_b32 s31, s28, 8
	s_lshl_b32 s4, s30, 8
	s_waitcnt lgkmcnt(0)
	v_mfma_f32_16x16x32_bf16 v[124:127], v[150:153], v[130:133], v[124:127]
	v_mfma_f32_16x16x32_bf16 v[120:123], v[150:153], v[134:137], v[120:123]
	v_mfma_f32_16x16x32_bf16 v[116:119], v[150:153], v[138:141], v[116:119]
	v_mfma_f32_16x16x32_bf16 v[112:115], v[150:153], v[142:145], v[112:115]
	v_mfma_f32_16x16x32_bf16 v[108:111], v[154:157], v[130:133], v[108:111]
	v_mfma_f32_16x16x32_bf16 v[104:107], v[154:157], v[134:137], v[104:107]
	v_mfma_f32_16x16x32_bf16 v[100:103], v[154:157], v[138:141], v[100:103]
	v_mfma_f32_16x16x32_bf16 v[96:99], v[154:157], v[142:145], v[96:99]
	v_mfma_f32_16x16x32_bf16 v[150:153], v[158:161], v[130:133], v[92:95]
	v_mfma_f32_16x16x32_bf16 v[84:87], v[158:161], v[134:137], v[84:87]
	v_mfma_f32_16x16x32_bf16 v[154:157], v[158:161], v[138:141], v[80:83]
	v_mfma_f32_16x16x32_bf16 v[76:79], v[158:161], v[142:145], v[76:79]
	v_mfma_f32_16x16x32_bf16 v[72:75], v[162:165], v[130:133], v[72:75]
	v_mfma_f32_16x16x32_bf16 v[68:71], v[162:165], v[134:137], v[68:71]
	v_mfma_f32_16x16x32_bf16 v[64:67], v[162:165], v[138:141], v[64:67]
	v_mfma_f32_16x16x32_bf16 v[158:161], v[162:165], v[142:145], v[60:63]
	s_nop 2
	v_add_u32_e32 v60, s9, v148
	v_add_u32_e32 v61, v60, v147
	v_add_u32_e32 v92, v60, v146
	ds_read_b128 v[162:165], v61 offset:32768
	ds_read_b128 v[186:189], v61 offset:34816
	ds_read_b128 v[190:193], v61 offset:36864
	ds_read_b128 v[194:197], v61 offset:38912
	ds_read_b128 v[60:63], v92
	ds_read_b128 v[80:83], v92 offset:2048
	ds_read_b128 v[146:149], v92 offset:4096
	ds_read_b128 v[198:201], v92 offset:6144
	v_mfma_f32_16x16x32_bf16 v[202:205], v[166:169], v[130:133], v[56:59]
	v_mfma_f32_16x16x32_bf16 v[206:209], v[166:169], v[134:137], v[52:55]
	v_mfma_f32_16x16x32_bf16 v[210:213], v[166:169], v[138:141], v[48:51]
	v_mfma_f32_16x16x32_bf16 v[44:47], v[166:169], v[142:145], v[44:47]
	v_mfma_f32_16x16x32_bf16 v[166:169], v[170:173], v[130:133], v[40:43]
	v_mfma_f32_16x16x32_bf16 v[36:39], v[170:173], v[134:137], v[36:39]
	v_mfma_f32_16x16x32_bf16 v[32:35], v[170:173], v[138:141], v[32:35]
	v_mfma_f32_16x16x32_bf16 v[214:217], v[174:177], v[130:133], v[24:27]
	v_mfma_f32_16x16x32_bf16 v[130:133], v[180:183], v[130:133], v[8:11]
	v_mfma_f32_16x16x32_bf16 v[4:7], v[180:183], v[134:137], v[4:7]
	v_mfma_f32_16x16x32_bf16 v[170:173], v[170:173], v[142:145], v[28:31]
	v_mfma_f32_16x16x32_bf16 v[218:221], v[174:177], v[134:137], v[20:23]
	v_mfma_f32_16x16x32_bf16 v[222:225], v[174:177], v[138:141], v[16:19]
	v_mfma_f32_16x16x32_bf16 v[174:177], v[174:177], v[142:145], v[12:15]
	v_mfma_f32_16x16x32_bf16 v[134:137], v[180:183], v[138:141], v[0:3]
	v_mfma_f32_16x16x32_bf16 v[138:141], v[180:183], v[142:145], v[88:91]
	s_nop 1
	ds_read_b128 v[0:3], v92 offset:8192
	ds_read_b128 v[12:15], v92 offset:10240
	ds_read_b128 v[142:145], v92 offset:12288
	ds_read_b128 v[180:183], v92 offset:14336
	s_waitcnt lgkmcnt(0)
	v_mfma_f32_16x16x32_bf16 v[124:127], v[60:63], v[162:165], v[124:127]
	v_mfma_f32_16x16x32_bf16 v[88:91], v[60:63], v[186:189], v[120:123]
	v_mfma_f32_16x16x32_bf16 v[56:59], v[60:63], v[190:193], v[116:119]
	v_mfma_f32_16x16x32_bf16 v[24:27], v[60:63], v[194:197], v[112:115]
	v_mfma_f32_16x16x32_bf16 v[120:123], v[80:83], v[162:165], v[108:111]
	v_mfma_f32_16x16x32_bf16 v[92:95], v[80:83], v[186:189], v[104:107]
	v_mfma_f32_16x16x32_bf16 v[60:63], v[80:83], v[190:193], v[100:103]
	v_mfma_f32_16x16x32_bf16 v[28:31], v[80:83], v[194:197], v[96:99]
	v_mfma_f32_16x16x32_bf16 v[112:115], v[146:149], v[162:165], v[150:153]
	v_mfma_f32_16x16x32_bf16 v[80:83], v[146:149], v[186:189], v[84:87]
	v_mfma_f32_16x16x32_bf16 v[48:51], v[146:149], v[190:193], v[154:157]
	v_mfma_f32_16x16x32_bf16 v[16:19], v[146:149], v[194:197], v[76:79]
	v_mfma_f32_16x16x32_bf16 v[116:119], v[198:201], v[162:165], v[72:75]
	v_mfma_f32_16x16x32_bf16 v[84:87], v[198:201], v[186:189], v[68:71]
	v_mfma_f32_16x16x32_bf16 v[52:55], v[198:201], v[190:193], v[64:67]
	v_mfma_f32_16x16x32_bf16 v[20:23], v[198:201], v[194:197], v[158:161]
	s_waitcnt vmcnt(0)
	v_mov_b32_e32 v154, v184
	s_waitcnt lgkmcnt(0)
	s_barrier
	v_mfma_f32_16x16x32_bf16 v[68:71], v[180:183], v[186:189], v[4:7]
	v_bfe_u32 v128, v154, 6, 2
	v_and_b32_e32 v152, 15, v154
	v_ashrrev_i32_e32 v153, 8, v154
	v_lshrrev_b32_e32 v4, 2, v154
	v_and_b32_e32 v155, 12, v4
	v_lshlrev_b32_e32 v4, 6, v128
	v_mfma_f32_16x16x32_bf16 v[104:107], v[0:3], v[162:165], v[202:205]
	s_cmpk_lt_u32 s31, 0x1101
	s_mov_b64 s[2:3], -1
	v_mfma_f32_16x16x32_bf16 v[72:75], v[0:3], v[186:189], v[206:209]
	v_mfma_f32_16x16x32_bf16 v[40:43], v[0:3], v[190:193], v[210:213]
	v_mfma_f32_16x16x32_bf16 v[8:11], v[0:3], v[194:197], v[44:47]
	v_mfma_f32_16x16x32_bf16 v[108:111], v[12:15], v[162:165], v[166:169]
	v_mfma_f32_16x16x32_bf16 v[76:79], v[12:15], v[186:189], v[36:39]
	v_mfma_f32_16x16x32_bf16 v[44:47], v[12:15], v[190:193], v[32:35]
	v_mfma_f32_16x16x32_bf16 v[12:15], v[12:15], v[194:197], v[170:173]
	v_mfma_f32_16x16x32_bf16 v[96:99], v[142:145], v[162:165], v[214:217]
	v_mfma_f32_16x16x32_bf16 v[64:67], v[142:145], v[186:189], v[218:221]
	v_mfma_f32_16x16x32_bf16 v[32:35], v[142:145], v[190:193], v[222:225]
	v_mfma_f32_16x16x32_bf16 v[0:3], v[142:145], v[194:197], v[174:177]
	v_mfma_f32_16x16x32_bf16 v[100:103], v[180:183], v[162:165], v[130:133]
	v_mfma_f32_16x16x32_bf16 v[36:39], v[180:183], v[190:193], v[134:137]
	s_nop 1
	v_or3_b32 v130, v4, v152, s4
	v_cvt_pk_bf16_f32 v132, v124, v125
	v_cvt_pk_bf16_f32 v133, v126, v127
	v_mfma_f32_16x16x32_bf16 v[4:7], v[180:183], v[194:197], v[138:141]
	s_cbranch_scc1 .LBB0_863
	v_lshl_or_b32 v136, v153, 7, v155
	v_add_u32_e32 v134, s31, v136
	v_cmp_lt_i32_e64 s[16:17], s52, v134
	s_and_saveexec_b64 s[2:3], s[16:17]
	s_xor_b64 s[4:5], exec, s[2:3]
	s_cbranch_execz .LBB0_148
	v_cmp_lt_u32_e32 vcc, s53, v134
	s_and_saveexec_b64 s[2:3], vcc
	s_xor_b64 s[6:7], exec, s[2:3]
	s_cbranch_execz .LBB0_145
	v_cmp_lt_u32_e32 vcc, s54, v134
	s_and_saveexec_b64 s[2:3], vcc
	s_xor_b64 s[8:9], exec, s[2:3]
	s_cbranch_execz .LBB0_142
	v_cmp_lt_u32_e32 vcc, s55, v134
	s_and_saveexec_b64 s[2:3], vcc
	s_xor_b64 s[10:11], exec, s[2:3]
	s_cbranch_execz .LBB0_139
	v_cmp_lt_u32_e32 vcc, s56, v134
	s_and_saveexec_b64 s[2:3], vcc
	s_xor_b64 s[2:3], exec, s[2:3]
	s_cbranch_execz .LBB0_134
	v_cmp_gt_u32_e32 vcc, s57, v134
	s_and_saveexec_b64 s[12:13], vcc
	s_cbranch_execz .LBB0_133
	v_ashrrev_i32_e32 v131, 31, v130
	v_lshlrev_b64 v[138:139], 7, v[130:131]
	v_lshl_add_u64 v[138:139], s[20:21], 0, v[138:139]
	v_mov_b32_e32 v135, v129
	v_lshl_add_u64 v[138:139], v[134:135], 2, v[138:139]
	v_add_co_u32_e32 v138, vcc, 0xefb000, v138
	s_nop 1
	v_addc_co_u32_e32 v139, vcc, 0, v139, vcc
	global_store_dwordx4 v[138:139], v[124:127], off offset:2048
